# v2 + P2 K-loop priorities swapped: loading wave at priority 1, MFMA wave at priority 0
# speedup vs baseline: 1.0026x; 1.0026x over previous
.LBB0_249:
	s_lshl_b32 s2, s87, 7
	s_add_u32 s12, s84, s2
	s_addc_u32 s13, s85, 0
	s_add_u32 s4, s12, 0x100
	s_addc_u32 s5, s13, 0
	s_and_b64 s[2:3], s[92:93], exec
	v_add_u32_e32 v140, s0, v1
	s_mul_i32 s2, s87, 0x188800
	ds_read_b128 v[148:151], v140
	ds_read_b128 v[152:155], v140 offset:256
	ds_read_b128 v[156:159], v140 offset:8192
	ds_read_b128 v[160:163], v140 offset:8448
	v_add_u32_e32 v140, s1, v1
	s_cselect_b32 s5, s5, s81
	s_cselect_b32 s4, s4, s80
	s_add_u32 s2, s88, s2
	ds_read_b128 v[164:167], v140
	ds_read_b128 v[168:171], v140 offset:256
	ds_read_b128 v[172:175], v140 offset:8192
	ds_read_b128 v[176:179], v140 offset:8448
	s_addc_u32 s3, s89, 0
	s_add_u32 s20, s2, 0x311000
	s_addc_u32 s21, s3, 0
	s_and_b64 s[2:3], s[92:93], exec
	s_cselect_b32 s92, s20, s86
	s_cselect_b32 s93, s21, s75
	s_add_u32 s94, s92, 0x188800
	s_addc_u32 s95, s93, 0
	s_add_u32 s2, s12, 0x104080
	s_addc_u32 s3, s13, 0
	v_lshl_add_u64 v[140:141], s[2:3], 0, v[130:131]
	s_add_i32 m0, s68, 0xc000
	ds_read_b128 v[180:183], v145
	ds_read_b128 v[184:187], v145 offset:1024
	ds_read_b128 v[188:191], v145 offset:2048
	ds_read_b128 v[192:195], v145 offset:3072
	ds_read_b128 v[196:199], v145 offset:4096
	ds_read_b128 v[200:203], v145 offset:5120
	ds_read_b128 v[204:207], v145 offset:6144
	ds_read_b128 v[208:211], v145 offset:7168
	global_load_lds_dwordx4 v[140:141], off
	v_lshl_add_u64 v[140:141], s[2:3], 0, v[134:135]
	s_add_i32 m0, s68, 0xe000
	s_nop 0
	global_load_lds_dwordx4 v[140:141], off
	s_waitcnt vmcnt(8)
	s_waitcnt lgkmcnt(0)
	s_barrier
	s_setprio 0
	s_waitcnt lgkmcnt(0)
	v_mfma_f32_16x16x32_bf16 v[126:129], v[148:151], v[180:183], v[126:129]
	v_mfma_f32_16x16x32_bf16 v[122:125], v[152:155], v[180:183], v[122:125]
	v_mfma_f32_16x16x32_bf16 v[118:121], v[148:151], v[188:191], v[118:121]
	v_mfma_f32_16x16x32_bf16 v[110:113], v[152:155], v[188:191], v[110:113]
	v_mfma_f32_16x16x32_bf16 v[102:105], v[148:151], v[196:199], v[102:105]
	v_mfma_f32_16x16x32_bf16 v[94:97], v[152:155], v[196:199], v[94:97]
	v_mfma_f32_16x16x32_bf16 v[86:89], v[148:151], v[204:207], v[86:89]
	v_mfma_f32_16x16x32_bf16 v[78:81], v[152:155], v[204:207], v[78:81]
	v_mfma_f32_16x16x32_bf16 v[126:129], v[156:159], v[184:187], v[126:129]
	v_mfma_f32_16x16x32_bf16 v[122:125], v[160:163], v[184:187], v[122:125]
	v_mfma_f32_16x16x32_bf16 v[118:121], v[156:159], v[192:195], v[118:121]
	v_mfma_f32_16x16x32_bf16 v[110:113], v[160:163], v[192:195], v[110:113]
	v_mfma_f32_16x16x32_bf16 v[102:105], v[156:159], v[200:203], v[102:105]
	v_mfma_f32_16x16x32_bf16 v[94:97], v[160:163], v[200:203], v[94:97]
	v_mfma_f32_16x16x32_bf16 v[86:89], v[156:159], v[208:211], v[86:89]
	v_mfma_f32_16x16x32_bf16 v[78:81], v[160:163], v[208:211], v[78:81]
	s_setprio 1
	s_setprio 0
	v_mfma_f32_16x16x32_bf16 v[114:117], v[164:167], v[180:183], v[114:117]
	v_mfma_f32_16x16x32_bf16 v[106:109], v[168:171], v[180:183], v[106:109]
	v_mfma_f32_16x16x32_bf16 v[98:101], v[164:167], v[188:191], v[98:101]
	v_mfma_f32_16x16x32_bf16 v[90:93], v[168:171], v[188:191], v[90:93]
	v_mfma_f32_16x16x32_bf16 v[82:85], v[164:167], v[196:199], v[82:85]
	v_mfma_f32_16x16x32_bf16 v[74:77], v[168:171], v[196:199], v[74:77]
	v_mfma_f32_16x16x32_bf16 v[70:73], v[164:167], v[204:207], v[70:73]
	v_mfma_f32_16x16x32_bf16 v[66:69], v[168:171], v[204:207], v[66:69]
	v_mfma_f32_16x16x32_bf16 v[114:117], v[172:175], v[184:187], v[114:117]
	v_mfma_f32_16x16x32_bf16 v[106:109], v[176:179], v[184:187], v[106:109]
	v_mfma_f32_16x16x32_bf16 v[98:101], v[172:175], v[192:195], v[98:101]
	v_mfma_f32_16x16x32_bf16 v[90:93], v[176:179], v[192:195], v[90:93]
	v_mfma_f32_16x16x32_bf16 v[82:85], v[172:175], v[200:203], v[82:85]
	v_mfma_f32_16x16x32_bf16 v[74:77], v[176:179], v[200:203], v[74:77]
	v_mfma_f32_16x16x32_bf16 v[70:73], v[172:175], v[208:211], v[70:73]
	v_mfma_f32_16x16x32_bf16 v[66:69], v[176:179], v[208:211], v[66:69]
	s_setprio 1
	s_barrier
	s_add_i32 s2, s0, s15
	v_lshl_add_u64 v[140:141], s[92:93], 0, v[132:133]
	s_mov_b32 m0, s2
	ds_read_b128 v[180:183], v145 offset:16384
	ds_read_b128 v[184:187], v145 offset:17408
	ds_read_b128 v[188:191], v145 offset:18432
	ds_read_b128 v[192:195], v145 offset:19456
	ds_read_b128 v[196:199], v145 offset:20480
	ds_read_b128 v[200:203], v145 offset:21504
	ds_read_b128 v[204:207], v145 offset:22528
	ds_read_b128 v[208:211], v145 offset:23552
	global_load_lds_dwordx4 v[140:141], off
	v_lshl_add_u64 v[212:213], s[92:93], 0, v[136:137]
	s_add_i32 m0, s2, 0x2000
	s_add_i32 s2, s1, s15
	global_load_lds_dwordx4 v[212:213], off
	v_lshl_add_u64 v[140:141], v[140:141], 0, s[10:11]
	s_mov_b32 m0, s2
	s_nop 0
	global_load_lds_dwordx4 v[140:141], off
	v_lshl_add_u64 v[140:141], v[212:213], 0, s[10:11]
	s_add_i32 m0, s2, 0x2000
	v_lshl_add_u64 v[212:213], s[4:5], 0, v[134:135]
	global_load_lds_dwordx4 v[140:141], off
	v_lshl_add_u64 v[140:141], s[4:5], 0, v[130:131]
	s_mov_b32 m0, s68
	s_nop 0
	global_load_lds_dwordx4 v[140:141], off
	s_mov_b32 m0, s69
	s_nop 0
	global_load_lds_dwordx4 v[212:213], off
	s_waitcnt vmcnt(8)
	s_waitcnt lgkmcnt(0)
	s_barrier
	s_setprio 0
	s_waitcnt lgkmcnt(0)
	v_mfma_f32_16x16x32_bf16 v[62:65], v[148:151], v[180:183], v[62:65]
	v_mfma_f32_16x16x32_bf16 v[58:61], v[152:155], v[180:183], v[58:61]
	v_mfma_f32_16x16x32_bf16 v[54:57], v[148:151], v[188:191], v[54:57]
	v_mfma_f32_16x16x32_bf16 v[46:49], v[152:155], v[188:191], v[46:49]
	v_mfma_f32_16x16x32_bf16 v[38:41], v[148:151], v[196:199], v[38:41]
	v_mfma_f32_16x16x32_bf16 v[30:33], v[152:155], v[196:199], v[30:33]
	v_mfma_f32_16x16x32_bf16 v[22:25], v[148:151], v[204:207], v[22:25]
	v_mfma_f32_16x16x32_bf16 v[14:17], v[152:155], v[204:207], v[14:17]
	v_mfma_f32_16x16x32_bf16 v[62:65], v[156:159], v[184:187], v[62:65]
	v_mfma_f32_16x16x32_bf16 v[58:61], v[160:163], v[184:187], v[58:61]
	v_mfma_f32_16x16x32_bf16 v[54:57], v[156:159], v[192:195], v[54:57]
	v_mfma_f32_16x16x32_bf16 v[46:49], v[160:163], v[192:195], v[46:49]
	v_mfma_f32_16x16x32_bf16 v[38:41], v[156:159], v[200:203], v[38:41]
	v_mfma_f32_16x16x32_bf16 v[30:33], v[160:163], v[200:203], v[30:33]
	v_mfma_f32_16x16x32_bf16 v[22:25], v[156:159], v[208:211], v[22:25]
	v_mfma_f32_16x16x32_bf16 v[14:17], v[160:163], v[208:211], v[14:17]
	s_setprio 1
	s_setprio 0
	v_mfma_f32_16x16x32_bf16 v[50:53], v[164:167], v[180:183], v[50:53]
	v_mfma_f32_16x16x32_bf16 v[42:45], v[168:171], v[180:183], v[42:45]
	v_mfma_f32_16x16x32_bf16 v[34:37], v[164:167], v[188:191], v[34:37]
	v_mfma_f32_16x16x32_bf16 v[26:29], v[168:171], v[188:191], v[26:29]
	v_mfma_f32_16x16x32_bf16 v[18:21], v[164:167], v[196:199], v[18:21]
	v_mfma_f32_16x16x32_bf16 v[10:13], v[168:171], v[196:199], v[10:13]
	v_mfma_f32_16x16x32_bf16 v[6:9], v[164:167], v[204:207], v[6:9]
	v_mfma_f32_16x16x32_bf16 v[2:5], v[168:171], v[204:207], v[2:5]
	v_mfma_f32_16x16x32_bf16 v[50:53], v[172:175], v[184:187], v[50:53]
	v_mfma_f32_16x16x32_bf16 v[42:45], v[176:179], v[184:187], v[42:45]
	v_mfma_f32_16x16x32_bf16 v[34:37], v[172:175], v[192:195], v[34:37]
	v_mfma_f32_16x16x32_bf16 v[26:29], v[176:179], v[192:195], v[26:29]
	v_mfma_f32_16x16x32_bf16 v[18:21], v[172:175], v[200:203], v[18:21]
	v_mfma_f32_16x16x32_bf16 v[10:13], v[176:179], v[200:203], v[10:13]
	v_mfma_f32_16x16x32_bf16 v[6:9], v[172:175], v[208:211], v[6:9]
	v_mfma_f32_16x16x32_bf16 v[2:5], v[176:179], v[208:211], v[2:5]
	s_setprio 1
	s_barrier
	s_add_i32 s12, 0, 0x18000
	v_add_u32_e32 v147, s12, v1
	s_add_i32 s13, 0, 0x1c000
	ds_read_b128 v[148:151], v147
	ds_read_b128 v[152:155], v147 offset:256
	ds_read_b128 v[156:159], v147 offset:8192
	ds_read_b128 v[160:163], v147 offset:8448
	v_add_u32_e32 v147, s13, v1
	ds_read_b128 v[164:167], v147
	ds_read_b128 v[168:171], v147 offset:256
	ds_read_b128 v[172:175], v147 offset:8192
	ds_read_b128 v[176:179], v147 offset:8448
	s_add_u32 s2, s4, 0x104000
	s_addc_u32 s3, s5, 0
	s_mov_b32 m0, s70
	v_lshl_add_u64 v[214:215], s[2:3], 0, v[130:131]
	ds_read_b128 v[180:183], v145 offset:32768
	ds_read_b128 v[184:187], v145 offset:33792
	ds_read_b128 v[188:191], v145 offset:34816
	ds_read_b128 v[192:195], v145 offset:35840
	ds_read_b128 v[196:199], v145 offset:36864
	ds_read_b128 v[200:203], v145 offset:37888
	ds_read_b128 v[204:207], v145 offset:38912
	ds_read_b128 v[208:211], v145 offset:39936
	global_load_lds_dwordx4 v[214:215], off
	v_lshl_add_u64 v[214:215], s[2:3], 0, v[134:135]
	s_mov_b32 m0, s71
	s_nop 0
	global_load_lds_dwordx4 v[214:215], off
	s_waitcnt vmcnt(8)
	s_waitcnt lgkmcnt(0)
	s_barrier
	s_setprio 0
	s_waitcnt lgkmcnt(0)
	v_mfma_f32_16x16x32_bf16 v[126:129], v[148:151], v[180:183], v[126:129]
	v_mfma_f32_16x16x32_bf16 v[122:125], v[152:155], v[180:183], v[122:125]
	v_mfma_f32_16x16x32_bf16 v[118:121], v[148:151], v[188:191], v[118:121]
	v_mfma_f32_16x16x32_bf16 v[110:113], v[152:155], v[188:191], v[110:113]
	v_mfma_f32_16x16x32_bf16 v[102:105], v[148:151], v[196:199], v[102:105]
	v_mfma_f32_16x16x32_bf16 v[94:97], v[152:155], v[196:199], v[94:97]
	v_mfma_f32_16x16x32_bf16 v[86:89], v[148:151], v[204:207], v[86:89]
	v_mfma_f32_16x16x32_bf16 v[78:81], v[152:155], v[204:207], v[78:81]
	v_mfma_f32_16x16x32_bf16 v[126:129], v[156:159], v[184:187], v[126:129]
	v_mfma_f32_16x16x32_bf16 v[122:125], v[160:163], v[184:187], v[122:125]
	v_mfma_f32_16x16x32_bf16 v[118:121], v[156:159], v[192:195], v[118:121]
	v_mfma_f32_16x16x32_bf16 v[110:113], v[160:163], v[192:195], v[110:113]
	v_mfma_f32_16x16x32_bf16 v[102:105], v[156:159], v[200:203], v[102:105]
	v_mfma_f32_16x16x32_bf16 v[94:97], v[160:163], v[200:203], v[94:97]
	v_mfma_f32_16x16x32_bf16 v[86:89], v[156:159], v[208:211], v[86:89]
	v_mfma_f32_16x16x32_bf16 v[78:81], v[160:163], v[208:211], v[78:81]
	s_setprio 1
	s_setprio 0
	v_mfma_f32_16x16x32_bf16 v[114:117], v[164:167], v[180:183], v[114:117]
	v_mfma_f32_16x16x32_bf16 v[106:109], v[168:171], v[180:183], v[106:109]
	v_mfma_f32_16x16x32_bf16 v[98:101], v[164:167], v[188:191], v[98:101]
	v_mfma_f32_16x16x32_bf16 v[90:93], v[168:171], v[188:191], v[90:93]
	v_mfma_f32_16x16x32_bf16 v[82:85], v[164:167], v[196:199], v[82:85]
	v_mfma_f32_16x16x32_bf16 v[74:77], v[168:171], v[196:199], v[74:77]
	v_mfma_f32_16x16x32_bf16 v[70:73], v[164:167], v[204:207], v[70:73]
	v_mfma_f32_16x16x32_bf16 v[66:69], v[168:171], v[204:207], v[66:69]
	v_mfma_f32_16x16x32_bf16 v[114:117], v[172:175], v[184:187], v[114:117]
	v_mfma_f32_16x16x32_bf16 v[106:109], v[176:179], v[184:187], v[106:109]
	v_mfma_f32_16x16x32_bf16 v[98:101], v[172:175], v[192:195], v[98:101]
	v_mfma_f32_16x16x32_bf16 v[90:93], v[176:179], v[192:195], v[90:93]
	v_mfma_f32_16x16x32_bf16 v[82:85], v[172:175], v[200:203], v[82:85]
	v_mfma_f32_16x16x32_bf16 v[74:77], v[176:179], v[200:203], v[74:77]
	v_mfma_f32_16x16x32_bf16 v[70:73], v[172:175], v[208:211], v[70:73]
	v_mfma_f32_16x16x32_bf16 v[66:69], v[176:179], v[208:211], v[66:69]
	s_setprio 1
	s_barrier
	s_add_i32 s2, s12, s15
	v_lshl_add_u64 v[214:215], s[94:95], 0, v[132:133]
	s_mov_b32 m0, s2
	ds_read_b128 v[180:183], v145 offset:49152
	ds_read_b128 v[184:187], v145 offset:50176
	ds_read_b128 v[188:191], v145 offset:51200
	ds_read_b128 v[192:195], v145 offset:52224
	ds_read_b128 v[196:199], v145 offset:53248
	ds_read_b128 v[200:203], v145 offset:54272
	ds_read_b128 v[204:207], v145 offset:55296
	ds_read_b128 v[208:211], v145 offset:56320
	global_load_lds_dwordx4 v[214:215], off
	s_add_i32 m0, s2, 0x2000
	s_add_u32 s2, s92, 0x189000
	v_lshl_add_u64 v[214:215], s[94:95], 0, v[136:137]
	s_addc_u32 s3, s93, 0
	s_add_i32 s4, s13, s15
	global_load_lds_dwordx4 v[214:215], off
	v_lshl_add_u64 v[214:215], s[2:3], 0, v[132:133]
	s_mov_b32 m0, s4
	v_lshl_add_u64 v[140:141], v[140:141], 0, s[52:53]
	global_load_lds_dwordx4 v[214:215], off
	v_lshl_add_u64 v[214:215], s[2:3], 0, v[136:137]
	s_add_i32 m0, s4, 0x2000
	s_nop 0
	global_load_lds_dwordx4 v[214:215], off
	s_mov_b32 m0, s8
	s_nop 0
	global_load_lds_dwordx4 v[140:141], off
	v_lshl_add_u64 v[140:141], v[212:213], 0, s[52:53]
	s_mov_b32 m0, s9
	s_nop 0
	global_load_lds_dwordx4 v[140:141], off
	s_waitcnt vmcnt(8)
	s_waitcnt lgkmcnt(0)
	s_barrier
	s_setprio 0
	s_waitcnt lgkmcnt(0)
	v_mfma_f32_16x16x32_bf16 v[62:65], v[148:151], v[180:183], v[62:65]
	v_mfma_f32_16x16x32_bf16 v[58:61], v[152:155], v[180:183], v[58:61]
	v_mfma_f32_16x16x32_bf16 v[54:57], v[148:151], v[188:191], v[54:57]
	v_mfma_f32_16x16x32_bf16 v[46:49], v[152:155], v[188:191], v[46:49]
	v_mfma_f32_16x16x32_bf16 v[38:41], v[148:151], v[196:199], v[38:41]
	v_mfma_f32_16x16x32_bf16 v[30:33], v[152:155], v[196:199], v[30:33]
	v_mfma_f32_16x16x32_bf16 v[22:25], v[148:151], v[204:207], v[22:25]
	v_mfma_f32_16x16x32_bf16 v[14:17], v[152:155], v[204:207], v[14:17]
	v_mfma_f32_16x16x32_bf16 v[62:65], v[156:159], v[184:187], v[62:65]
	v_mfma_f32_16x16x32_bf16 v[58:61], v[160:163], v[184:187], v[58:61]
	v_mfma_f32_16x16x32_bf16 v[54:57], v[156:159], v[192:195], v[54:57]
	v_mfma_f32_16x16x32_bf16 v[46:49], v[160:163], v[192:195], v[46:49]
	v_mfma_f32_16x16x32_bf16 v[38:41], v[156:159], v[200:203], v[38:41]
	v_mfma_f32_16x16x32_bf16 v[30:33], v[160:163], v[200:203], v[30:33]
	v_mfma_f32_16x16x32_bf16 v[22:25], v[156:159], v[208:211], v[22:25]
	v_mfma_f32_16x16x32_bf16 v[14:17], v[160:163], v[208:211], v[14:17]
	s_setprio 1
	s_setprio 0
	v_mfma_f32_16x16x32_bf16 v[50:53], v[164:167], v[180:183], v[50:53]
	v_mfma_f32_16x16x32_bf16 v[42:45], v[168:171], v[180:183], v[42:45]
	v_mfma_f32_16x16x32_bf16 v[34:37], v[164:167], v[188:191], v[34:37]
	v_mfma_f32_16x16x32_bf16 v[26:29], v[168:171], v[188:191], v[26:29]
	v_mfma_f32_16x16x32_bf16 v[18:21], v[164:167], v[196:199], v[18:21]
	v_mfma_f32_16x16x32_bf16 v[10:13], v[168:171], v[196:199], v[10:13]
	v_mfma_f32_16x16x32_bf16 v[6:9], v[164:167], v[204:207], v[6:9]
	v_mfma_f32_16x16x32_bf16 v[2:5], v[168:171], v[204:207], v[2:5]
	v_mfma_f32_16x16x32_bf16 v[50:53], v[172:175], v[184:187], v[50:53]
	v_mfma_f32_16x16x32_bf16 v[42:45], v[176:179], v[184:187], v[42:45]
	v_mfma_f32_16x16x32_bf16 v[34:37], v[172:175], v[192:195], v[34:37]
	v_mfma_f32_16x16x32_bf16 v[26:29], v[176:179], v[192:195], v[26:29]
	v_mfma_f32_16x16x32_bf16 v[18:21], v[172:175], v[200:203], v[18:21]
	v_mfma_f32_16x16x32_bf16 v[10:13], v[176:179], v[200:203], v[10:13]
	v_mfma_f32_16x16x32_bf16 v[6:9], v[172:175], v[208:211], v[6:9]
	v_mfma_f32_16x16x32_bf16 v[2:5], v[176:179], v[208:211], v[2:5]
	s_setprio 1
	s_barrier
	s_add_i32 s2, s87, 2
	s_cmp_gt_u32 s87, 61
	s_cbranch_scc1 .LBB0_255
	s_mov_b32 s87, s2
	s_branch .LBB0_220
